# P2: E2 operand reads issued up front (11 of 12), E3 8-lane reductions via DPP adds instead of six serialized ds_bpermute
# speedup vs baseline: 1.0101x; 1.0013x over previous
; __device__ __forceinline__ unsigned pk2(float lo, float hi) { f32x2_t v = {lo, hi}; bf16x2_t b = __builtin_convertvector(v, bf16x2_t); return __builtin_bit_cast(unsigned, b); }
; __device__ __forceinline__ float bflo(unsigned v) { return __uint_as_float(v << 16); }
; __device__ __forceinline__ float bfhi(unsigned v) { return __uint_as_float(v & 0xffff0000u); }
; __device__ __forceinline__ float fexp(float x) { return __builtin_amdgcn_exp2f(x * 1.44269504088896f); }
; __device__ void rwkv_prep_item(const Params& p, char* lds_, int item, PrepRaw& raw, int next_item) {
;     ...
;     auto ldshift = [&](int col, float (&o)[8], const u32x4 cur) {
;       u32x4 prv; prv.x = prv.y = prv.z = prv.w = 0u;
;       if (hasprev) prv = *(const u32x4*)(prow - PBW + col);
;       const f32x4 m0 = *(const f32x4*)(p.shift_mu + col), m1 = *(const f32x4*)(p.shift_mu + col + 4);
;       const unsigned cw[4] = {cur.x, cur.y, cur.z, cur.w}, pw[4] = {prv.x, prv.y, prv.z, prv.w};
; #pragma unroll
;       for (int q = 0; q < 4; ++q) {
;         const float c0 = bflo(cw[q]), c1 = bfhi(cw[q]), p0 = bflo(pw[q]), p1 = bfhi(pw[q]);
;         const float mu0 = (q < 2) ? m0[2 * q] : m1[2 * q - 4], mu1 = (q < 2) ? m0[2 * q + 1] : m1[2 * q - 3];
;         o[2 * q] = c0 + (p0 - c0) * mu0;
;         o[2 * q + 1] = c1 + (p1 - c1) * mu1;
;       }
;     };
;     ldshift(hd * 64 + cg8, rr, raw.cur[0]);
;     ldshift(512 + hd * 64 + cg8, kk_, raw.cur[1]);
;     ldshift(1024 + hd * 64 + cg8, vv, raw.cur[2]);
;     float wd[8], ad[8];
;     ldshift(1536 + cg8, wd, raw.cur[3]);
;     ldshift(1600 + cg8, ad, raw.cur[4]);
;     u32x4 w;
;     float th[8];
; #pragma unroll
;     for (int e = 0; e < 8; ++e) th[e] = 1.f - 2.f * __builtin_amdgcn_rcpf(1.f + fexp(2.f * wd[e]));
;     w.x = pk2(th[0], th[1]); w.y = pk2(th[2], th[3]); w.z = pk2(th[4], th[5]); w.w = pk2(th[6], th[7]);
.LBB0_291:
	s_or_b64 exec, exec, s[56:57]
	s_waitcnt vmcnt(6)
	v_lshlrev_b32_e32 v118, 16, v10
	v_and_b32_e32 v155, 0xffff0000, v10
	s_waitcnt vmcnt(0) lgkmcnt(0)
	v_lshlrev_b32_e32 v156, 16, v102
	v_and_b32_e32 v102, 0xffff0000, v102
	v_sub_f32_e32 v156, v156, v118
	v_sub_f32_e32 v102, v102, v155
	s_waitcnt vmcnt(0)
	v_fmac_f32_e32 v118, v110, v156
	v_fmac_f32_e32 v155, v111, v102
	v_lshlrev_b32_e32 v110, 16, v11
	v_lshlrev_b32_e32 v102, 16, v103
	v_and_b32_e32 v111, 0xffff0000, v11
	v_and_b32_e32 v103, 0xffff0000, v103
	v_sub_f32_e32 v102, v102, v110
	v_fmac_f32_e32 v110, v112, v102
	v_sub_f32_e32 v102, v103, v111
	v_fmac_f32_e32 v111, v113, v102
	v_lshlrev_b32_e32 v112, 16, v12
	v_lshlrev_b32_e32 v102, 16, v104
	v_and_b32_e32 v113, 0xffff0000, v12
	v_and_b32_e32 v103, 0xffff0000, v104
	v_sub_f32_e32 v102, v102, v112
	v_fmac_f32_e32 v112, v106, v102
	v_sub_f32_e32 v102, v103, v113
	v_fmac_f32_e32 v113, v107, v102
	v_and_b32_e32 v102, 0xffff0000, v105
	v_and_b32_e32 v156, 0xffff0000, v13
	v_sub_f32_e32 v102, v102, v156
	v_lshlrev_b32_e32 v103, 16, v105
	v_lshlrev_b32_e32 v157, 16, v13
	v_fmac_f32_e32 v156, v109, v102
	v_and_b32_e32 v104, 0xffff0000, v2
	v_lshlrev_b32_e32 v102, 16, v90
	v_and_b32_e32 v90, 0xffff0000, v90
	v_sub_f32_e32 v103, v103, v157
	v_lshlrev_b32_e32 v105, 16, v2
	v_sub_f32_e32 v90, v90, v104
	v_fmac_f32_e32 v157, v108, v103
	v_sub_f32_e32 v102, v102, v105
	v_fmac_f32_e32 v104, v99, v90
	v_lshlrev_b32_e32 v103, 16, v3
	v_lshlrev_b32_e32 v90, 16, v91
	v_fmac_f32_e32 v105, v98, v102
	v_and_b32_e32 v102, 0xffff0000, v3
	v_and_b32_e32 v91, 0xffff0000, v91
	v_sub_f32_e32 v90, v90, v103
	v_fmac_f32_e32 v103, v100, v90
	v_sub_f32_e32 v90, v91, v102
	v_fmac_f32_e32 v102, v101, v90
	v_lshlrev_b32_e32 v99, 16, v4
	v_lshlrev_b32_e32 v90, 16, v92
	v_and_b32_e32 v98, 0xffff0000, v4
	v_and_b32_e32 v91, 0xffff0000, v92
	v_sub_f32_e32 v90, v90, v99
	v_fmac_f32_e32 v99, v94, v90
	v_sub_f32_e32 v90, v91, v98
	v_fmac_f32_e32 v98, v95, v90
	v_and_b32_e32 v90, 0xffff0000, v93
	v_and_b32_e32 v92, 0xffff0000, v5
	v_lshlrev_b32_e32 v91, 16, v93
	v_lshlrev_b32_e32 v93, 16, v5
	v_sub_f32_e32 v90, v90, v92
	v_sub_f32_e32 v91, v91, v93
	v_fmac_f32_e32 v92, v97, v90
	v_and_b32_e32 v90, 0xffff0000, v6
	v_lshlrev_b32_e32 v94, 16, v78
	v_and_b32_e32 v78, 0xffff0000, v78
	v_fmac_f32_e32 v93, v96, v91
	v_lshlrev_b32_e32 v91, 16, v6
	v_sub_f32_e32 v78, v78, v90
	v_sub_f32_e32 v94, v94, v91
	v_fmac_f32_e32 v90, v87, v78
	v_lshlrev_b32_e32 v87, 16, v7
	v_lshlrev_b32_e32 v78, 16, v79
	v_fmac_f32_e32 v91, v86, v94
	v_and_b32_e32 v86, 0xffff0000, v7
	v_and_b32_e32 v79, 0xffff0000, v79
	v_sub_f32_e32 v78, v78, v87
	v_fmac_f32_e32 v87, v88, v78
	v_sub_f32_e32 v78, v79, v86
	v_fmac_f32_e32 v86, v89, v78
	v_lshlrev_b32_e32 v89, 16, v8
	v_lshlrev_b32_e32 v78, 16, v80
	v_and_b32_e32 v88, 0xffff0000, v8
	v_and_b32_e32 v79, 0xffff0000, v80
	v_sub_f32_e32 v78, v78, v89
	v_fmac_f32_e32 v89, v78, v82
	v_sub_f32_e32 v78, v79, v88
	v_fmac_f32_e32 v88, v78, v83
	v_and_b32_e32 v78, 0xffff0000, v81
	v_lshlrev_b32_e32 v79, 16, v81
	v_and_b32_e32 v82, 0xffff0000, v9
	v_lshlrev_b32_e32 v83, 16, v9
	v_sub_f32_e32 v79, v79, v83
	v_sub_f32_e32 v78, v78, v82
	v_fmac_f32_e32 v83, v79, v84
	v_fmac_f32_e32 v82, v78, v85
	v_add_f32_e32 v84, v118, v118
	v_add_f32_e32 v85, v155, v155
	v_add_f32_e32 v100, v110, v110
	v_add_f32_e32 v101, v111, v111
	v_add_f32_e32 v106, v112, v112
	v_add_f32_e32 v107, v113, v113
	v_add_f32_e32 v108, v157, v157
	v_add_f32_e32 v109, v156, v156
	v_mul_f32_e32 v84, 0x3fb8aa3b, v84
	v_mul_f32_e32 v85, 0x3fb8aa3b, v85
	v_mul_f32_e32 v100, 0x3fb8aa3b, v100
	v_mul_f32_e32 v101, 0x3fb8aa3b, v101
	v_mul_f32_e32 v106, 0x3fb8aa3b, v106
	v_mul_f32_e32 v107, 0x3fb8aa3b, v107
	v_mul_f32_e32 v108, 0x3fb8aa3b, v108
	v_mul_f32_e32 v109, 0x3fb8aa3b, v109
	v_exp_f32_e32 v84, v84
	v_exp_f32_e32 v85, v85
	v_exp_f32_e32 v100, v100
	v_exp_f32_e32 v101, v101
	v_exp_f32_e32 v106, v106
	v_exp_f32_e32 v107, v107
	v_exp_f32_e32 v108, v108
	v_exp_f32_e32 v109, v109
	v_lshlrev_b32_e32 v110, 16, v14
	v_and_b32_e32 v111, 0xffff0000, v14
	v_lshlrev_b32_e32 v112, 16, v74
	v_and_b32_e32 v113, 0xffff0000, v74
	v_pk_add_f32 v[112:113], v[112:113], v[110:111] neg_lo:[0,1] neg_hi:[0,1]
	v_add_f32_e32 v84, 1.0, v84
	v_add_f32_e32 v85, 1.0, v85
	v_add_f32_e32 v100, 1.0, v100
	v_add_f32_e32 v101, 1.0, v101
	v_add_f32_e32 v106, 1.0, v106
	v_add_f32_e32 v107, 1.0, v107
	v_add_f32_e32 v108, 1.0, v108
	v_add_f32_e32 v109, 1.0, v109
	v_lshlrev_b32_e32 v74, 16, v75
	v_and_b32_e32 v75, 0xffff0000, v75
	v_rcp_f32_e32 v84, v84
	v_rcp_f32_e32 v85, v85
	v_rcp_f32_e32 v100, v100
	v_rcp_f32_e32 v101, v101
	v_rcp_f32_e32 v106, v106
	v_rcp_f32_e32 v107, v107
	v_rcp_f32_e32 v108, v108
	v_rcp_f32_e32 v109, v109
	v_pk_fma_f32 v[84:85], v[84:85], 2.0, 1.0 op_sel_hi:[1,0,0] neg_lo:[1,0,0] neg_hi:[1,0,0]
	v_pk_fma_f32 v[100:101], v[100:101], 2.0, 1.0 op_sel_hi:[1,0,0] neg_lo:[1,0,0] neg_hi:[1,0,0]
	v_pk_fma_f32 v[106:107], v[106:107], 2.0, 1.0 op_sel_hi:[1,0,0] neg_lo:[1,0,0] neg_hi:[1,0,0]
	v_pk_fma_f32 v[108:109], v[108:109], 2.0, 1.0 op_sel_hi:[1,0,0] neg_lo:[1,0,0] neg_hi:[1,0,0]
	v_add_lshl_u32 v118, s55, v240, 7
	v_mul_f32_e32 v67, v67, v104
	v_mul_f32_e32 v66, v66, v105
	v_mul_f32_e32 v68, v68, v103
	v_mul_f32_e32 v69, v69, v102
	s_add_i32 s90, s54, s50
	s_waitcnt vmcnt(0)
; __device__ __forceinline__ unsigned pk2(float lo, float hi) { f32x2_t v = {lo, hi}; bf16x2_t b = __builtin_convertvector(v, bf16x2_t); return __builtin_bit_cast(unsigned, b); }
; __device__ void rwkv_prep_item(const Params& p, char* lds_, int item, PrepRaw& raw, int next_item) {
;     ...
;       pdb[q] = *(const f32x4*)(p.decay_bias + cbp + 4 * q); pib[q] = *(const f32x4*)(p.iclr_bias + cbp + 4 * q);
;       pkk[q] = *(const f32x4*)(p.k_k + cbp + 4 * q); pka[q] = *(const f32x4*)(p.k_a + cbp + 4 * q); prk[q] = *(const f32x4*)(p.r_k + cbp + 4 * q);
;     ...
;     w.x = pk2(th[0], th[1]); w.y = pk2(th[2], th[3]); w.z = pk2(th[4], th[5]); w.w = pk2(th[6], th[7]);
;     *(u32x4*)(TW + t * LD + cg8) = w;
;     w.x = pk2(ad[0], ad[1]); w.y = pk2(ad[2], ad[3]); w.z = pk2(ad[4], ad[5]); w.w = pk2(ad[6], ad[7]);
;     *(u32x4*)(AD + t * LD + cg8) = w;
;     *(u32x4*)(DUs + t * LD + cg8) = *(const u32x4*)(p.DUt + (size_t)(hd * 64 + t) * 64 + cg8);
;     *(u32x4*)(IUs + t * LD + cg8) = *(const u32x4*)(p.IUt + (size_t)(hd * 64 + t) * 64 + cg8);
;   }
;   __syncthreads();
;   const int it = wave >> 1, jt0 = (wave & 1) * 2, mr = lane & 15, mg = lane >> 4;
;   const int mi = it * 16 + mr;
;   {
;     f32x4 a1[2], a2[2]; zero2(a1); zero2(a2);
;     mm_nt(TW, DUs, a1, wave, lane);
;     mm_nt(AD, IUs, a2, wave, lane);
; #pragma unroll
;     for (int jj = 0; jj < 2; ++jj) {
;       *(f32x4*)(Zw + mi * 68 + (jt0 + jj) * 16 + 4 * mg) = a1[jj];
;       *(f32x4*)(Za + mi * 68 + (jt0 + jj) * 16 + 4 * mg) = a2[jj];
;     }
;   }
	v_pk_fma_f32 v[94:95], v[200:201], v[112:113], v[110:111]
	v_lshlrev_b32_e32 v110, 16, v15
	v_and_b32_e32 v111, 0xffff0000, v15
	v_pk_add_f32 v[74:75], v[74:75], v[110:111] neg_lo:[0,1] neg_hi:[0,1]
	s_nop 0
	v_pk_fma_f32 v[96:97], v[202:203], v[74:75], v[110:111]
	v_lshlrev_b32_e32 v74, 16, v16
	v_and_b32_e32 v75, 0xffff0000, v16
	v_lshlrev_b32_e32 v110, 16, v76
	v_and_b32_e32 v111, 0xffff0000, v76
	v_pk_add_f32 v[110:111], v[110:111], v[74:75] neg_lo:[0,1] neg_hi:[0,1]
	v_lshlrev_b32_e32 v76, 16, v17
	v_pk_fma_f32 v[78:79], v[192:193], v[110:111], v[74:75]
	v_lshlrev_b32_e32 v74, 16, v77
	v_and_b32_e32 v75, 0xffff0000, v77
	v_and_b32_e32 v77, 0xffff0000, v17
	v_pk_add_f32 v[74:75], v[74:75], v[76:77] neg_lo:[0,1] neg_hi:[0,1]
	s_nop 0
	v_pk_fma_f32 v[80:81], v[194:195], v[74:75], v[76:77]
	v_cvt_pk_bf16_f32 v74, v84, v85
	v_cvt_pk_bf16_f32 v75, v100, v101
	v_cvt_pk_bf16_f32 v76, v106, v107
	v_cvt_pk_bf16_f32 v77, v108, v109
	ds_write_b128 v117, v[74:77]
	v_cvt_pk_bf16_f32 v74, v94, v95
	v_cvt_pk_bf16_f32 v75, v96, v97
	v_cvt_pk_bf16_f32 v76, v78, v79
	v_cvt_pk_bf16_f32 v77, v80, v81
	ds_write_b128 v117, v[74:77] offset:9216
	v_mul_f32_e32 v85, v67, v67
	v_fmac_f32_e32 v85, v66, v66
	v_fmac_f32_e32 v85, v68, v68
	v_fmac_f32_e32 v85, v69, v69
	ds_write_b128 v117, v[158:161] offset:18432
	ds_write_b128 v117, v[196:199] offset:27648
	s_and_b32 s94, s90, 0x1c0
	v_add_lshl_u32 v196, s94, v240, 7
	v_mov_b32_e32 v197, 0
	v_mov_b64_e32 v[158:159], v[196:197]
	v_lshl_add_u64 v[196:197], v[136:137], 0, v[196:197]
	global_load_dwordx4 v[196:199], v[196:197], off
	v_lshl_add_u64 v[158:159], v[134:135], 0, v[158:159]
	global_load_dwordx4 v[158:161], v[158:159], off
	v_or_b32_e32 v58, s55, v116
	v_lshlrev_b32_e32 v58, 2, v58
	global_load_dwordx4 v[34:37], v58, s[62:63] offset:16
	global_load_dwordx4 v[38:41], v58, s[62:63]
	global_load_dwordx4 v[54:57], v58, s[80:81] offset:16
	global_load_dwordx4 v[70:73], v58, s[80:81]
	global_load_dwordx4 v[46:49], v58, s[64:65] offset:16
	global_load_dwordx4 v[50:53], v58, s[66:67] offset:16
	global_load_dwordx4 v[62:65], v58, s[66:67]
	global_load_dwordx4 v[42:45], v58, s[82:83] offset:16
	global_load_dwordx4 v[58:61], v58, s[82:83]
	s_waitcnt lgkmcnt(0)
	s_barrier
	ds_read_b128 v[74:77], v162
	ds_read_b128 v[78:81], v163
	ds_read_b128 v[94:97], v163 offset:2304
	ds_read_b128 v[2:5], v162 offset:64
	ds_read_b128 v[106:109], v164
	ds_read_b128 v[6:9], v165 offset:2304
	ds_read_b128 v[10:13], v166
	ds_read_b128 v[110:113], v167
	ds_read_b128 v[14:17], v167 offset:2304
	ds_read_b128 v[130:133], v166 offset:64
	ds_read_b128 v[192:195], v168
	s_waitcnt lgkmcnt(9)
	v_mfma_f32_16x16x32_bf16 v[78:81], v[78:81], v[74:77], 0
	s_waitcnt lgkmcnt(8)
	v_mfma_f32_16x16x32_bf16 v[94:97], v[94:97], v[74:77], 0
	ds_read_b128 v[74:77], v169 offset:2304
	s_waitcnt lgkmcnt(7)
	v_mfma_f32_16x16x32_bf16 v[78:81], v[106:109], v[2:5], v[78:81]
	s_waitcnt lgkmcnt(6)
	v_mfma_f32_16x16x32_bf16 v[94:97], v[6:9], v[2:5], v[94:97]
	s_waitcnt lgkmcnt(4)
	v_mfma_f32_16x16x32_bf16 v[110:113], v[110:113], v[10:13], 0
	s_waitcnt lgkmcnt(3)
	v_mfma_f32_16x16x32_bf16 v[14:17], v[14:17], v[10:13], 0
	s_waitcnt lgkmcnt(1)
	v_mfma_f32_16x16x32_bf16 v[110:113], v[192:195], v[130:133], v[110:113]
	s_waitcnt lgkmcnt(0)
	v_mfma_f32_16x16x32_bf16 v[14:17], v[74:77], v[130:133], v[14:17]
	s_nop 7
	ds_write_b128 v170, v[78:81]
	ds_write_b128 v170, v[94:97] offset:64
	s_nop 3
	ds_write_b128 v171, v[110:113]
	ds_write_b128 v171, v[14:17] offset:64
	s_waitcnt lgkmcnt(0)
	s_barrier
; __device__ __forceinline__ float fsigmoid(float x) { return __builtin_amdgcn_rcpf(1.f + fexp(-x)); }
; __device__ void rwkv_prep_item(const Params& p, char* lds_, int item, PrepRaw& raw, int next_item) {
;     ...
;     for (int e = 0; e < 8; ++e) {
;       const float zw = Zw[t * 68 + cg8 + e] + pdb[e >> 2][e & 3];
;       const float za = Za[t * 68 + cg8 + e] + pib[e >> 2][e & 3];
;       lw[e] = -0.6065306597126334f * fsigmoid(zw);
;       ai[e] = fsigmoid(za);
;       kk[e] = kk_[e] * pkk[e >> 2][e & 3];
;       k2[e] = kk_[e] * (1.f + (ai[e] - 1.f) * pka[e >> 2][e & 3]);
;       ss += kk[e] * kk[e];
;       bon += rr[e] * k2[e] * prk[e >> 2][e & 3];
;     }
;     ss += __shfl_xor(ss, 1); ss += __shfl_xor(ss, 2); ss += __shfl_xor(ss, 4);
;     bon += __shfl_xor(bon, 1); bon += __shfl_xor(bon, 2); bon += __shfl_xor(bon, 4);
;     const float inv = __builtin_amdgcn_rsqf(fmaxf(ss, 1e-24f));
; #pragma unroll
;     for (int e = 0; e < 8; ++e) { const float kn = kk[e] * inv; av[e] = -kn; bv[e] = kn * ai[e]; }
;   }
;   __builtin_amdgcn_sched_barrier(0);
;   if (next_item < 4096) prep_load(p, next_item, raw);
	ds_read_b128 v[74:77], v172
	ds_read_b128 v[78:81], v173
	s_waitcnt vmcnt(0) lgkmcnt(0)
	v_add_f32_e32 v70, v70, v78
	v_mul_f32_e32 v70, 0xbfb8aa3b, v70
	v_exp_f32_e32 v70, v70
	s_nop 0
	v_add_f32_e32 v70, 1.0, v70
	v_rcp_f32_e32 v70, v70
	s_nop 0
	v_add_f32_e32 v78, -1.0, v70
	v_fma_f32 v62, v62, v78, 1.0
	v_mul_f32_e32 v62, v105, v62
	v_mul_f32_e32 v78, v91, v62
	v_fma_f32 v84, v58, v78, 0
	v_add_f32_e32 v58, v71, v79
	v_mul_f32_e32 v58, 0xbfb8aa3b, v58
	v_exp_f32_e32 v58, v58
	s_nop 0
	v_add_f32_e32 v58, 1.0, v58
	v_rcp_f32_e32 v71, v58
	s_nop 0
	v_add_f32_e32 v58, -1.0, v71
	v_fma_f32 v58, v63, v58, 1.0
	v_mul_f32_e32 v63, v104, v58
	v_mul_f32_e32 v58, v90, v63
	v_fmac_f32_e32 v84, v59, v58
	v_add_f32_e32 v58, v72, v80
	v_mul_f32_e32 v58, 0xbfb8aa3b, v58
	v_exp_f32_e32 v58, v58
	s_nop 0
	v_add_f32_e32 v58, 1.0, v58
	v_rcp_f32_e32 v72, v58
	s_nop 0
	v_add_f32_e32 v58, -1.0, v72
	v_fma_f32 v58, v64, v58, 1.0
	v_mul_f32_e32 v64, v103, v58
	v_mul_f32_e32 v58, v87, v64
	v_fmac_f32_e32 v84, v60, v58
	v_add_f32_e32 v58, v73, v81
	v_mul_f32_e32 v58, 0xbfb8aa3b, v58
	v_exp_f32_e32 v58, v58
	s_nop 0
	v_add_f32_e32 v58, 1.0, v58
	v_rcp_f32_e32 v73, v58
	s_nop 0
	v_add_f32_e32 v58, -1.0, v73
	v_fma_f32 v58, v65, v58, 1.0
	v_mul_f32_e32 v65, v102, v58
	v_mul_f32_e32 v58, v86, v65
	v_fmac_f32_e32 v84, v61, v58
	ds_read_b128 v[58:61], v176
	ds_read_b128 v[78:81], v177
	s_waitcnt lgkmcnt(0)
	v_add_f32_e32 v54, v54, v78
	v_mul_f32_e32 v54, 0xbfb8aa3b, v54
	v_exp_f32_e32 v54, v54
	v_mul_f32_e32 v78, v46, v99
	v_fmac_f32_e32 v85, v78, v78
	v_add_f32_e32 v54, 1.0, v54
	v_rcp_f32_e32 v54, v54
	s_nop 0
	v_add_f32_e32 v46, -1.0, v54
	v_fma_f32 v46, v50, v46, 1.0
	v_mul_f32_e32 v46, v99, v46
	v_mul_f32_e32 v50, v89, v46
	v_fmac_f32_e32 v84, v42, v50
	v_add_f32_e32 v42, v55, v79
	v_mul_f32_e32 v42, 0xbfb8aa3b, v42
	v_exp_f32_e32 v42, v42
	v_mul_f32_e32 v55, v47, v98
	v_fmac_f32_e32 v85, v55, v55
	v_mul_f32_e32 v79, v49, v92
	v_add_f32_e32 v42, 1.0, v42
	v_rcp_f32_e32 v50, v42
	s_nop 0
	v_add_f32_e32 v42, -1.0, v50
	v_fma_f32 v42, v51, v42, 1.0
	v_mul_f32_e32 v47, v98, v42
	v_mul_f32_e32 v42, v88, v47
	v_fmac_f32_e32 v84, v43, v42
	v_add_f32_e32 v42, v56, v80
	v_mul_f32_e32 v42, 0xbfb8aa3b, v42
	v_exp_f32_e32 v42, v42
	v_mul_f32_e32 v56, v48, v93
	v_fmac_f32_e32 v85, v56, v56
	v_fmac_f32_e32 v85, v79, v79
	v_add_f32_e32 v42, 1.0, v42
	v_rcp_f32_e32 v51, v42
	s_nop 0
	v_add_f32_e32 v42, -1.0, v51
	v_fma_f32 v42, v52, v42, 1.0
	v_mul_f32_e32 v52, v93, v42
	v_mul_f32_e32 v42, v83, v52
	v_fmac_f32_e32 v84, v44, v42
	v_add_f32_e32 v42, v57, v81
	v_mul_f32_e32 v42, 0xbfb8aa3b, v42
	v_exp_f32_e32 v42, v42
	s_nop 0
	v_add_f32_e32 v42, 1.0, v42
	v_rcp_f32_e32 v57, v42
	s_nop 0
	v_add_f32_e32 v42, -1.0, v57
	v_fma_f32 v42, v53, v42, 1.0
	v_mul_f32_e32 v53, v92, v42
	v_mul_f32_e32 v42, v82, v53
	v_fmac_f32_e32 v84, v45, v42
	s_nop 1
	v_add_f32_dpp v42, v85, v85 quad_perm:[1,0,3,2] row_mask:0xf bank_mask:0xf
	v_add_f32_dpp v43, v84, v84 quad_perm:[1,0,3,2] row_mask:0xf bank_mask:0xf
	s_nop 1
	v_add_f32_dpp v80, v42, v42 quad_perm:[2,3,0,1] row_mask:0xf bank_mask:0xf
	v_add_f32_dpp v48, v43, v43 quad_perm:[2,3,0,1] row_mask:0xf bank_mask:0xf
	s_nop 1
	v_mov_b32_dpp v81, v80 row_half_mirror row_mask:0xf bank_mask:0xf
	v_mov_b32_dpp v49, v48 row_half_mirror row_mask:0xf bank_mask:0xf
	s_cmpk_gt_i32 s90, 0xfff
	s_cselect_b64 s[56:57], -1, 0
	v_mov_b64_e32 v[44:45], v[20:21]
	s_and_b64 vcc, exec, s[56:57]
	v_mov_b64_e32 v[42:43], v[18:19]
	s_cbranch_vccnz .LBB0_293
	s_ashr_i32 s58, s90, 9
	s_lshl_b32 s74, s90, 6
	s_ashr_i32 s59, s58, 31
	s_and_b32 s74, s74, 0xfc0
	s_lshl_b64 s[58:59], s[58:59], 12
	v_add_u32_e32 v118, s74, v240
	v_lshl_add_u64 v[2:3], s[58:59], 0, v[118:119]
	v_mov_b64_e32 v[4:5], s[78:79]
	s_and_b32 s55, s90, 0x1c0
	v_mad_u64_u32 v[10:11], s[58:59], v2, s53, v[4:5]
	v_mad_i32_i24 v11, v3, s53, v11
	s_lshl_b32 s74, s55, 1
	v_lshl_add_u64 v[2:3], v[10:11], 0, s[74:75]
	v_mov_b32_e32 v155, v119
	v_lshl_add_u64 v[12:13], v[2:3], 0, v[154:155]
	v_lshl_add_u64 v[14:15], v[10:11], 0, v[154:155]
	global_load_dwordx4 v[6:9], v[12:13], off
	global_load_dwordx4 v[2:5], v[12:13], off offset:1024
	global_load_dwordx4 v[42:45], v[12:13], off offset:2048
	s_nop 0
	global_load_dwordx4 v[10:13], v[14:15], off offset:3072
	s_nop 0
	global_load_dwordx4 v[14:17], v[14:15], off offset:3200
